# gate pass epilogue: bias pre-multiplied so sigmoid argument is one fma; scale+round offset fused into one fma
# speedup vs baseline: 1.0112x; 1.0064x over previous
; DI float sigm(float x) { return __builtin_amdgcn_rcpf(1.f + __expf(-x)); }
; DI void phase_merge(const Params& p, int l, LAS char* lds) {
;     ...
;         if (gate) {
; #pragma unroll
;             for (int ni = 0; ni < 4; ++ni) {
;                 const f32x4 bv = bvv[ni];
; #pragma unroll
;                 for (int mi = 0; mi < 4; ++mi) {
;                     const f32x4 a = acc[mi][ni] + bv;
;                     const unsigned q0 = (unsigned)(fmaxf(sigm(a[0]) * 255.f, 1.f) + 0.5f), q1 = (unsigned)(fmaxf(sigm(a[1]) * 255.f, 1.f) + 0.5f);
;                     const unsigned q2 = (unsigned)(fmaxf(sigm(a[2]) * 255.f, 1.f) + 0.5f), q3 = (unsigned)(fmaxf(sigm(a[3]) * 255.f, 1.f) + 0.5f);
;                     st[(mi * 4 + ni) * 256] = q0 | (q1 << 8) | (q2 << 16) | (q3 << 24);
;                 }
;             }
.Lgpk15_dn:
	s_setprio 0
	s_lshl_b32 s5, s55, 2
	s_add_u32 s5, s5, s54
	s_lshl_b32 s5, s5, 14
	s_add_u32 s58, s60, s5
	s_addc_u32 s59, s61, 0
	s_mov_b32 s5, 0xbfb8aa3b
	s_mov_b32 s6, 0x437f0000
	v_mul_f32_e32 v66, 0xbfb8aa3b, v66
	v_mul_f32_e32 v68, 0xbfb8aa3b, v68
	v_mul_f32_e32 v69, 0xbfb8aa3b, v69
	v_mul_f32_e32 v93, 0xbfb8aa3b, v93
	v_mul_f32_e32 v146, 0xbfb8aa3b, v146
	v_mul_f32_e32 v147, 0xbfb8aa3b, v147
	v_mul_f32_e32 v148, 0xbfb8aa3b, v148
	v_mul_f32_e32 v160, 0xbfb8aa3b, v160
	v_mul_f32_e32 v161, 0xbfb8aa3b, v161
	v_mul_f32_e32 v182, 0xbfb8aa3b, v182
	v_mul_f32_e32 v183, 0xbfb8aa3b, v183
	v_mul_f32_e32 v184, 0xbfb8aa3b, v184
	v_mul_f32_e32 v185, 0xbfb8aa3b, v185
	v_mul_f32_e32 v71, 0xbfb8aa3b, v71
	v_mul_f32_e32 v73, 0xbfb8aa3b, v73
	v_mul_f32_e32 v75, 0xbfb8aa3b, v75
	v_fma_f32 v186, v62, s5, v66
	v_fma_f32 v187, v63, s5, v68
	v_fma_f32 v188, v64, s5, v69
	v_fma_f32 v189, v65, s5, v93
	v_exp_f32_e32 v186, v186
	v_exp_f32_e32 v187, v187
	v_exp_f32_e32 v188, v188
	v_exp_f32_e32 v189, v189
	v_add_f32_e32 v186, 1.0, v186
	v_add_f32_e32 v187, 1.0, v187
	v_add_f32_e32 v188, 1.0, v188
	v_add_f32_e32 v189, 1.0, v189
	v_rcp_f32_e32 v186, v186
	v_rcp_f32_e32 v187, v187
	v_rcp_f32_e32 v188, v188
	v_rcp_f32_e32 v189, v189
	v_fma_f32 v186, v186, s6, 0.5
	v_fma_f32 v187, v187, s6, 0.5
	v_fma_f32 v188, v188, s6, 0.5
	v_fma_f32 v189, v189, s6, 0.5
	v_max_f32_e32 v186, 1.5, v186
	v_max_f32_e32 v187, 1.5, v187
	v_max_f32_e32 v188, 1.5, v188
	v_max_f32_e32 v189, 1.5, v189
	v_cvt_u32_f32_e32 v186, v186
	v_cvt_u32_f32_e32 v187, v187
	v_cvt_u32_f32_sdwa v188, v188 dst_sel:WORD_1 dst_unused:UNUSED_PAD src0_sel:DWORD
	v_cvt_u32_f32_sdwa v189, v189 dst_sel:BYTE_3 dst_unused:UNUSED_PAD src0_sel:DWORD
	v_lshl_or_b32 v186, v187, 8, v186
	s_nop 0
	v_or3_b32 v186, v186, v188, v189
	global_store_dword v1, v186, s[58:59] offset:0
	v_fma_f32 v190, v58, s5, v146
	v_fma_f32 v191, v59, s5, v147
	v_fma_f32 v192, v60, s5, v148
	v_fma_f32 v193, v61, s5, v160
	v_exp_f32_e32 v190, v190
	v_exp_f32_e32 v191, v191
	v_exp_f32_e32 v192, v192
	v_exp_f32_e32 v193, v193
	v_add_f32_e32 v190, 1.0, v190
	v_add_f32_e32 v191, 1.0, v191
	v_add_f32_e32 v192, 1.0, v192
	v_add_f32_e32 v193, 1.0, v193
	v_rcp_f32_e32 v190, v190
	v_rcp_f32_e32 v191, v191
	v_rcp_f32_e32 v192, v192
	v_rcp_f32_e32 v193, v193
	v_fma_f32 v190, v190, s6, 0.5
	v_fma_f32 v191, v191, s6, 0.5
	v_fma_f32 v192, v192, s6, 0.5
	v_fma_f32 v193, v193, s6, 0.5
	v_max_f32_e32 v190, 1.5, v190
	v_max_f32_e32 v191, 1.5, v191
	v_max_f32_e32 v192, 1.5, v192
	v_max_f32_e32 v193, 1.5, v193
	v_cvt_u32_f32_e32 v190, v190
	v_cvt_u32_f32_e32 v191, v191
	v_cvt_u32_f32_sdwa v192, v192 dst_sel:WORD_1 dst_unused:UNUSED_PAD src0_sel:DWORD
	v_cvt_u32_f32_sdwa v193, v193 dst_sel:BYTE_3 dst_unused:UNUSED_PAD src0_sel:DWORD
	v_lshl_or_b32 v190, v191, 8, v190
	s_nop 0
	v_or3_b32 v190, v190, v192, v193
	global_store_dword v1, v190, s[58:59] offset:1024
	v_fma_f32 v186, v54, s5, v161
	v_fma_f32 v187, v55, s5, v182
	v_fma_f32 v188, v56, s5, v183
	v_fma_f32 v189, v57, s5, v184
	v_exp_f32_e32 v186, v186
	v_exp_f32_e32 v187, v187
	v_exp_f32_e32 v188, v188
	v_exp_f32_e32 v189, v189
	v_add_f32_e32 v186, 1.0, v186
	v_add_f32_e32 v187, 1.0, v187
	v_add_f32_e32 v188, 1.0, v188
	v_add_f32_e32 v189, 1.0, v189
	v_rcp_f32_e32 v186, v186
	v_rcp_f32_e32 v187, v187
	v_rcp_f32_e32 v188, v188
	v_rcp_f32_e32 v189, v189
	v_fma_f32 v186, v186, s6, 0.5
	v_fma_f32 v187, v187, s6, 0.5
	v_fma_f32 v188, v188, s6, 0.5
	v_fma_f32 v189, v189, s6, 0.5
	v_max_f32_e32 v186, 1.5, v186
	v_max_f32_e32 v187, 1.5, v187
	v_max_f32_e32 v188, 1.5, v188
	v_max_f32_e32 v189, 1.5, v189
	v_cvt_u32_f32_e32 v186, v186
	v_cvt_u32_f32_e32 v187, v187
	v_cvt_u32_f32_sdwa v188, v188 dst_sel:WORD_1 dst_unused:UNUSED_PAD src0_sel:DWORD
	v_cvt_u32_f32_sdwa v189, v189 dst_sel:BYTE_3 dst_unused:UNUSED_PAD src0_sel:DWORD
	v_lshl_or_b32 v186, v187, 8, v186
	s_nop 0
	v_or3_b32 v186, v186, v188, v189
	global_store_dword v1, v186, s[58:59] offset:2048
	v_fma_f32 v190, v50, s5, v185
	v_fma_f32 v191, v51, s5, v71
	v_fma_f32 v192, v52, s5, v73
	v_fma_f32 v193, v53, s5, v75
	v_exp_f32_e32 v190, v190
	v_exp_f32_e32 v191, v191
	v_exp_f32_e32 v192, v192
	v_exp_f32_e32 v193, v193
	v_add_f32_e32 v190, 1.0, v190
	v_add_f32_e32 v191, 1.0, v191
	v_add_f32_e32 v192, 1.0, v192
	v_add_f32_e32 v193, 1.0, v193
	v_rcp_f32_e32 v190, v190
	v_rcp_f32_e32 v191, v191
	v_rcp_f32_e32 v192, v192
	v_rcp_f32_e32 v193, v193
	v_fma_f32 v190, v190, s6, 0.5
	v_fma_f32 v191, v191, s6, 0.5
	v_fma_f32 v192, v192, s6, 0.5
	v_fma_f32 v193, v193, s6, 0.5
	v_max_f32_e32 v190, 1.5, v190
	v_max_f32_e32 v191, 1.5, v191
	v_max_f32_e32 v192, 1.5, v192
	v_max_f32_e32 v193, 1.5, v193
	v_cvt_u32_f32_e32 v190, v190
	v_cvt_u32_f32_e32 v191, v191
	v_cvt_u32_f32_sdwa v192, v192 dst_sel:WORD_1 dst_unused:UNUSED_PAD src0_sel:DWORD
	v_cvt_u32_f32_sdwa v193, v193 dst_sel:BYTE_3 dst_unused:UNUSED_PAD src0_sel:DWORD
	v_lshl_or_b32 v190, v191, 8, v190
	s_nop 0
	v_or3_b32 v190, v190, v192, v193
	global_store_dword v1, v190, s[58:59] offset:3072
	s_add_u32 s58, s58, 0x1000
	s_addc_u32 s59, s59, 0
	v_fma_f32 v186, v46, s5, v66
	v_fma_f32 v187, v47, s5, v68
	v_fma_f32 v188, v48, s5, v69
	v_fma_f32 v189, v49, s5, v93
	v_exp_f32_e32 v186, v186
	v_exp_f32_e32 v187, v187
	v_exp_f32_e32 v188, v188
	v_exp_f32_e32 v189, v189
	v_add_f32_e32 v186, 1.0, v186
	v_add_f32_e32 v187, 1.0, v187
	v_add_f32_e32 v188, 1.0, v188
	v_add_f32_e32 v189, 1.0, v189
	v_rcp_f32_e32 v186, v186
	v_rcp_f32_e32 v187, v187
	v_rcp_f32_e32 v188, v188
	v_rcp_f32_e32 v189, v189
	v_fma_f32 v186, v186, s6, 0.5
	v_fma_f32 v187, v187, s6, 0.5
	v_fma_f32 v188, v188, s6, 0.5
	v_fma_f32 v189, v189, s6, 0.5
; DI float sigm(float x) { return __builtin_amdgcn_rcpf(1.f + __expf(-x)); }
; DI void phase_merge(const Params& p, int l, LAS char* lds) {
;     ...
;         if (gate) {
; #pragma unroll
;             for (int ni = 0; ni < 4; ++ni) {
;                 const f32x4 bv = bvv[ni];
; #pragma unroll
;                 for (int mi = 0; mi < 4; ++mi) {
;                     const f32x4 a = acc[mi][ni] + bv;
;                     const unsigned q0 = (unsigned)(fmaxf(sigm(a[0]) * 255.f, 1.f) + 0.5f), q1 = (unsigned)(fmaxf(sigm(a[1]) * 255.f, 1.f) + 0.5f);
;                     const unsigned q2 = (unsigned)(fmaxf(sigm(a[2]) * 255.f, 1.f) + 0.5f), q3 = (unsigned)(fmaxf(sigm(a[3]) * 255.f, 1.f) + 0.5f);
;                     st[(mi * 4 + ni) * 256] = q0 | (q1 << 8) | (q2 << 16) | (q3 << 24);
;                 }
;             }
	v_max_f32_e32 v186, 1.5, v186
	v_max_f32_e32 v187, 1.5, v187
	v_max_f32_e32 v188, 1.5, v188
	v_max_f32_e32 v189, 1.5, v189
	v_cvt_u32_f32_e32 v186, v186
	v_cvt_u32_f32_e32 v187, v187
	v_cvt_u32_f32_sdwa v188, v188 dst_sel:WORD_1 dst_unused:UNUSED_PAD src0_sel:DWORD
	v_cvt_u32_f32_sdwa v189, v189 dst_sel:BYTE_3 dst_unused:UNUSED_PAD src0_sel:DWORD
	v_lshl_or_b32 v186, v187, 8, v186
	s_nop 0
	v_or3_b32 v186, v186, v188, v189
	global_store_dword v1, v186, s[58:59] offset:0
	v_fma_f32 v190, v42, s5, v146
	v_fma_f32 v191, v43, s5, v147
	v_fma_f32 v192, v44, s5, v148
	v_fma_f32 v193, v45, s5, v160
	v_exp_f32_e32 v190, v190
	v_exp_f32_e32 v191, v191
	v_exp_f32_e32 v192, v192
	v_exp_f32_e32 v193, v193
	v_add_f32_e32 v190, 1.0, v190
	v_add_f32_e32 v191, 1.0, v191
	v_add_f32_e32 v192, 1.0, v192
	v_add_f32_e32 v193, 1.0, v193
	v_rcp_f32_e32 v190, v190
	v_rcp_f32_e32 v191, v191
	v_rcp_f32_e32 v192, v192
	v_rcp_f32_e32 v193, v193
	v_fma_f32 v190, v190, s6, 0.5
	v_fma_f32 v191, v191, s6, 0.5
	v_fma_f32 v192, v192, s6, 0.5
	v_fma_f32 v193, v193, s6, 0.5
	v_max_f32_e32 v190, 1.5, v190
	v_max_f32_e32 v191, 1.5, v191
	v_max_f32_e32 v192, 1.5, v192
	v_max_f32_e32 v193, 1.5, v193
	v_cvt_u32_f32_e32 v190, v190
	v_cvt_u32_f32_e32 v191, v191
	v_cvt_u32_f32_sdwa v192, v192 dst_sel:WORD_1 dst_unused:UNUSED_PAD src0_sel:DWORD
	v_cvt_u32_f32_sdwa v193, v193 dst_sel:BYTE_3 dst_unused:UNUSED_PAD src0_sel:DWORD
	v_lshl_or_b32 v190, v191, 8, v190
	s_nop 0
	v_or3_b32 v190, v190, v192, v193
	global_store_dword v1, v190, s[58:59] offset:1024
	v_fma_f32 v186, v38, s5, v161
	v_fma_f32 v187, v39, s5, v182
	v_fma_f32 v188, v40, s5, v183
	v_fma_f32 v189, v41, s5, v184
	v_exp_f32_e32 v186, v186
	v_exp_f32_e32 v187, v187
	v_exp_f32_e32 v188, v188
	v_exp_f32_e32 v189, v189
	v_add_f32_e32 v186, 1.0, v186
	v_add_f32_e32 v187, 1.0, v187
	v_add_f32_e32 v188, 1.0, v188
	v_add_f32_e32 v189, 1.0, v189
	v_rcp_f32_e32 v186, v186
	v_rcp_f32_e32 v187, v187
	v_rcp_f32_e32 v188, v188
	v_rcp_f32_e32 v189, v189
	v_fma_f32 v186, v186, s6, 0.5
	v_fma_f32 v187, v187, s6, 0.5
	v_fma_f32 v188, v188, s6, 0.5
	v_fma_f32 v189, v189, s6, 0.5
	v_max_f32_e32 v186, 1.5, v186
	v_max_f32_e32 v187, 1.5, v187
	v_max_f32_e32 v188, 1.5, v188
	v_max_f32_e32 v189, 1.5, v189
	v_cvt_u32_f32_e32 v186, v186
	v_cvt_u32_f32_e32 v187, v187
	v_cvt_u32_f32_sdwa v188, v188 dst_sel:WORD_1 dst_unused:UNUSED_PAD src0_sel:DWORD
	v_cvt_u32_f32_sdwa v189, v189 dst_sel:BYTE_3 dst_unused:UNUSED_PAD src0_sel:DWORD
	v_lshl_or_b32 v186, v187, 8, v186
	s_nop 0
	v_or3_b32 v186, v186, v188, v189
	global_store_dword v1, v186, s[58:59] offset:2048
	v_fma_f32 v190, v34, s5, v185
	v_fma_f32 v191, v35, s5, v71
	v_fma_f32 v192, v36, s5, v73
	v_fma_f32 v193, v37, s5, v75
	v_exp_f32_e32 v190, v190
	v_exp_f32_e32 v191, v191
	v_exp_f32_e32 v192, v192
	v_exp_f32_e32 v193, v193
	v_add_f32_e32 v190, 1.0, v190
	v_add_f32_e32 v191, 1.0, v191
	v_add_f32_e32 v192, 1.0, v192
	v_add_f32_e32 v193, 1.0, v193
	v_rcp_f32_e32 v190, v190
	v_rcp_f32_e32 v191, v191
	v_rcp_f32_e32 v192, v192
	v_rcp_f32_e32 v193, v193
	v_fma_f32 v190, v190, s6, 0.5
	v_fma_f32 v191, v191, s6, 0.5
	v_fma_f32 v192, v192, s6, 0.5
	v_fma_f32 v193, v193, s6, 0.5
	v_max_f32_e32 v190, 1.5, v190
	v_max_f32_e32 v191, 1.5, v191
	v_max_f32_e32 v192, 1.5, v192
	v_max_f32_e32 v193, 1.5, v193
	v_cvt_u32_f32_e32 v190, v190
	v_cvt_u32_f32_e32 v191, v191
	v_cvt_u32_f32_sdwa v192, v192 dst_sel:WORD_1 dst_unused:UNUSED_PAD src0_sel:DWORD
	v_cvt_u32_f32_sdwa v193, v193 dst_sel:BYTE_3 dst_unused:UNUSED_PAD src0_sel:DWORD
	v_lshl_or_b32 v190, v191, 8, v190
	s_nop 0
	v_or3_b32 v190, v190, v192, v193
	global_store_dword v1, v190, s[58:59] offset:3072
	s_add_u32 s58, s58, 0x1000
	s_addc_u32 s59, s59, 0
	v_fma_f32 v186, v30, s5, v66
	v_fma_f32 v187, v31, s5, v68
	v_fma_f32 v188, v32, s5, v69
	v_fma_f32 v189, v33, s5, v93
	v_exp_f32_e32 v186, v186
	v_exp_f32_e32 v187, v187
	v_exp_f32_e32 v188, v188
	v_exp_f32_e32 v189, v189
	v_add_f32_e32 v186, 1.0, v186
	v_add_f32_e32 v187, 1.0, v187
	v_add_f32_e32 v188, 1.0, v188
	v_add_f32_e32 v189, 1.0, v189
	v_rcp_f32_e32 v186, v186
	v_rcp_f32_e32 v187, v187
	v_rcp_f32_e32 v188, v188
	v_rcp_f32_e32 v189, v189
	v_fma_f32 v186, v186, s6, 0.5
	v_fma_f32 v187, v187, s6, 0.5
	v_fma_f32 v188, v188, s6, 0.5
	v_fma_f32 v189, v189, s6, 0.5
	v_max_f32_e32 v186, 1.5, v186
	v_max_f32_e32 v187, 1.5, v187
	v_max_f32_e32 v188, 1.5, v188
	v_max_f32_e32 v189, 1.5, v189
	v_cvt_u32_f32_e32 v186, v186
	v_cvt_u32_f32_e32 v187, v187
	v_cvt_u32_f32_sdwa v188, v188 dst_sel:WORD_1 dst_unused:UNUSED_PAD src0_sel:DWORD
	v_cvt_u32_f32_sdwa v189, v189 dst_sel:BYTE_3 dst_unused:UNUSED_PAD src0_sel:DWORD
	v_lshl_or_b32 v186, v187, 8, v186
	s_nop 0
	v_or3_b32 v186, v186, v188, v189
	global_store_dword v1, v186, s[58:59] offset:0
	v_fma_f32 v190, v26, s5, v146
	v_fma_f32 v191, v27, s5, v147
	v_fma_f32 v192, v28, s5, v148
	v_fma_f32 v193, v29, s5, v160
	v_exp_f32_e32 v190, v190
	v_exp_f32_e32 v191, v191
	v_exp_f32_e32 v192, v192
	v_exp_f32_e32 v193, v193
	v_add_f32_e32 v190, 1.0, v190
	v_add_f32_e32 v191, 1.0, v191
	v_add_f32_e32 v192, 1.0, v192
	v_add_f32_e32 v193, 1.0, v193
	v_rcp_f32_e32 v190, v190
	v_rcp_f32_e32 v191, v191
	v_rcp_f32_e32 v192, v192
	v_rcp_f32_e32 v193, v193
	v_fma_f32 v190, v190, s6, 0.5
	v_fma_f32 v191, v191, s6, 0.5
	v_fma_f32 v192, v192, s6, 0.5
	v_fma_f32 v193, v193, s6, 0.5
	v_max_f32_e32 v190, 1.5, v190
	v_max_f32_e32 v191, 1.5, v191
	v_max_f32_e32 v192, 1.5, v192
	v_max_f32_e32 v193, 1.5, v193
	v_cvt_u32_f32_e32 v190, v190
	v_cvt_u32_f32_e32 v191, v191
	v_cvt_u32_f32_sdwa v192, v192 dst_sel:WORD_1 dst_unused:UNUSED_PAD src0_sel:DWORD
; DI float sigm(float x) { return __builtin_amdgcn_rcpf(1.f + __expf(-x)); }
; DI void phase_merge(const Params& p, int l, LAS char* lds) {
;     ...
;     for (int f = 0; f < nops; ++f) {
;         const bool gate = f < 4 * ntl;
;         int br, i;
;         if (gate) { br = f / ntl; i = vb + (f - br * ntl) * G; } else { const int f2 = f - 4 * ntl; br = f2 & 3; i = vb + (f2 >> 2) * G; }
;         const int mt = i >> 3, nt = i & 7;
;         const bool has_next = f + 1 < nops;
;         const GOp g = op_of(f), gn = op_of(has_next ? f + 1 : f);
;     ...
;         if (gate) {
; #pragma unroll
;             for (int ni = 0; ni < 4; ++ni) {
;                 const f32x4 bv = bvv[ni];
; #pragma unroll
;                 for (int mi = 0; mi < 4; ++mi) {
;                     const f32x4 a = acc[mi][ni] + bv;
;                     const unsigned q0 = (unsigned)(fmaxf(sigm(a[0]) * 255.f, 1.f) + 0.5f), q1 = (unsigned)(fmaxf(sigm(a[1]) * 255.f, 1.f) + 0.5f);
;                     const unsigned q2 = (unsigned)(fmaxf(sigm(a[2]) * 255.f, 1.f) + 0.5f), q3 = (unsigned)(fmaxf(sigm(a[3]) * 255.f, 1.f) + 0.5f);
;                     st[(mi * 4 + ni) * 256] = q0 | (q1 << 8) | (q2 << 16) | (q3 << 24);
;                 }
;             }
	v_cvt_u32_f32_sdwa v193, v193 dst_sel:BYTE_3 dst_unused:UNUSED_PAD src0_sel:DWORD
	v_lshl_or_b32 v190, v191, 8, v190
	s_nop 0
	v_or3_b32 v190, v190, v192, v193
	global_store_dword v1, v190, s[58:59] offset:1024
	v_fma_f32 v186, v22, s5, v161
	v_fma_f32 v187, v23, s5, v182
	v_fma_f32 v188, v24, s5, v183
	v_fma_f32 v189, v25, s5, v184
	v_exp_f32_e32 v186, v186
	v_exp_f32_e32 v187, v187
	v_exp_f32_e32 v188, v188
	v_exp_f32_e32 v189, v189
	v_add_f32_e32 v186, 1.0, v186
	v_add_f32_e32 v187, 1.0, v187
	v_add_f32_e32 v188, 1.0, v188
	v_add_f32_e32 v189, 1.0, v189
	v_rcp_f32_e32 v186, v186
	v_rcp_f32_e32 v187, v187
	v_rcp_f32_e32 v188, v188
	v_rcp_f32_e32 v189, v189
	v_fma_f32 v186, v186, s6, 0.5
	v_fma_f32 v187, v187, s6, 0.5
	v_fma_f32 v188, v188, s6, 0.5
	v_fma_f32 v189, v189, s6, 0.5
	v_max_f32_e32 v186, 1.5, v186
	v_max_f32_e32 v187, 1.5, v187
	v_max_f32_e32 v188, 1.5, v188
	v_max_f32_e32 v189, 1.5, v189
	v_cvt_u32_f32_e32 v186, v186
	v_cvt_u32_f32_e32 v187, v187
	v_cvt_u32_f32_sdwa v188, v188 dst_sel:WORD_1 dst_unused:UNUSED_PAD src0_sel:DWORD
	v_cvt_u32_f32_sdwa v189, v189 dst_sel:BYTE_3 dst_unused:UNUSED_PAD src0_sel:DWORD
	v_lshl_or_b32 v186, v187, 8, v186
	s_nop 0
	v_or3_b32 v186, v186, v188, v189
	global_store_dword v1, v186, s[58:59] offset:2048
	v_fma_f32 v190, v18, s5, v185
	v_fma_f32 v191, v19, s5, v71
	v_fma_f32 v192, v20, s5, v73
	v_fma_f32 v193, v21, s5, v75
	v_exp_f32_e32 v190, v190
	v_exp_f32_e32 v191, v191
	v_exp_f32_e32 v192, v192
	v_exp_f32_e32 v193, v193
	v_add_f32_e32 v190, 1.0, v190
	v_add_f32_e32 v191, 1.0, v191
	v_add_f32_e32 v192, 1.0, v192
	v_add_f32_e32 v193, 1.0, v193
	v_rcp_f32_e32 v190, v190
	v_rcp_f32_e32 v191, v191
	v_rcp_f32_e32 v192, v192
	v_rcp_f32_e32 v193, v193
	v_fma_f32 v190, v190, s6, 0.5
	v_fma_f32 v191, v191, s6, 0.5
	v_fma_f32 v192, v192, s6, 0.5
	v_fma_f32 v193, v193, s6, 0.5
	v_max_f32_e32 v190, 1.5, v190
	v_max_f32_e32 v191, 1.5, v191
	v_max_f32_e32 v192, 1.5, v192
	v_max_f32_e32 v193, 1.5, v193
	v_cvt_u32_f32_e32 v190, v190
	v_cvt_u32_f32_e32 v191, v191
	v_cvt_u32_f32_sdwa v192, v192 dst_sel:WORD_1 dst_unused:UNUSED_PAD src0_sel:DWORD
	v_cvt_u32_f32_sdwa v193, v193 dst_sel:BYTE_3 dst_unused:UNUSED_PAD src0_sel:DWORD
	v_lshl_or_b32 v190, v191, 8, v190
	s_nop 0
	v_or3_b32 v190, v190, v192, v193
	global_store_dword v1, v190, s[58:59] offset:3072
	s_add_u32 s58, s58, 0x1000
	s_addc_u32 s59, s59, 0
	v_fma_f32 v186, v14, s5, v66
	v_fma_f32 v187, v15, s5, v68
	v_fma_f32 v188, v16, s5, v69
	v_fma_f32 v189, v17, s5, v93
	v_exp_f32_e32 v186, v186
	v_exp_f32_e32 v187, v187
	v_exp_f32_e32 v188, v188
	v_exp_f32_e32 v189, v189
	v_add_f32_e32 v186, 1.0, v186
	v_add_f32_e32 v187, 1.0, v187
	v_add_f32_e32 v188, 1.0, v188
	v_add_f32_e32 v189, 1.0, v189
	v_rcp_f32_e32 v186, v186
	v_rcp_f32_e32 v187, v187
	v_rcp_f32_e32 v188, v188
	v_rcp_f32_e32 v189, v189
	v_fma_f32 v186, v186, s6, 0.5
	v_fma_f32 v187, v187, s6, 0.5
	v_fma_f32 v188, v188, s6, 0.5
	v_fma_f32 v189, v189, s6, 0.5
	v_max_f32_e32 v186, 1.5, v186
	v_max_f32_e32 v187, 1.5, v187
	v_max_f32_e32 v188, 1.5, v188
	v_max_f32_e32 v189, 1.5, v189
	v_cvt_u32_f32_e32 v186, v186
	v_cvt_u32_f32_e32 v187, v187
	v_cvt_u32_f32_sdwa v188, v188 dst_sel:WORD_1 dst_unused:UNUSED_PAD src0_sel:DWORD
	v_cvt_u32_f32_sdwa v189, v189 dst_sel:BYTE_3 dst_unused:UNUSED_PAD src0_sel:DWORD
	v_lshl_or_b32 v186, v187, 8, v186
	s_nop 0
	v_or3_b32 v186, v186, v188, v189
	global_store_dword v1, v186, s[58:59] offset:0
	v_fma_f32 v190, v10, s5, v146
	v_fma_f32 v191, v11, s5, v147
	v_fma_f32 v192, v12, s5, v148
	v_fma_f32 v193, v13, s5, v160
	v_exp_f32_e32 v190, v190
	v_exp_f32_e32 v191, v191
	v_exp_f32_e32 v192, v192
	v_exp_f32_e32 v193, v193
	v_add_f32_e32 v190, 1.0, v190
	v_add_f32_e32 v191, 1.0, v191
	v_add_f32_e32 v192, 1.0, v192
	v_add_f32_e32 v193, 1.0, v193
	v_rcp_f32_e32 v190, v190
	v_rcp_f32_e32 v191, v191
	v_rcp_f32_e32 v192, v192
	v_rcp_f32_e32 v193, v193
	v_fma_f32 v190, v190, s6, 0.5
	v_fma_f32 v191, v191, s6, 0.5
	v_fma_f32 v192, v192, s6, 0.5
	v_fma_f32 v193, v193, s6, 0.5
	v_max_f32_e32 v190, 1.5, v190
	v_max_f32_e32 v191, 1.5, v191
	v_max_f32_e32 v192, 1.5, v192
	v_max_f32_e32 v193, 1.5, v193
	v_cvt_u32_f32_e32 v190, v190
	v_cvt_u32_f32_e32 v191, v191
	v_cvt_u32_f32_sdwa v192, v192 dst_sel:WORD_1 dst_unused:UNUSED_PAD src0_sel:DWORD
	v_cvt_u32_f32_sdwa v193, v193 dst_sel:BYTE_3 dst_unused:UNUSED_PAD src0_sel:DWORD
	v_lshl_or_b32 v190, v191, 8, v190
	s_nop 0
	v_or3_b32 v190, v190, v192, v193
	global_store_dword v1, v190, s[58:59] offset:1024
	v_fma_f32 v186, v6, s5, v161
	v_fma_f32 v187, v7, s5, v182
	v_fma_f32 v188, v8, s5, v183
	v_fma_f32 v189, v9, s5, v184
	v_exp_f32_e32 v186, v186
	v_exp_f32_e32 v187, v187
	v_exp_f32_e32 v188, v188
	v_exp_f32_e32 v189, v189
	v_add_f32_e32 v186, 1.0, v186
	v_add_f32_e32 v187, 1.0, v187
	v_add_f32_e32 v188, 1.0, v188
	v_add_f32_e32 v189, 1.0, v189
	v_rcp_f32_e32 v186, v186
	v_rcp_f32_e32 v187, v187
	v_rcp_f32_e32 v188, v188
	v_rcp_f32_e32 v189, v189
	v_fma_f32 v186, v186, s6, 0.5
	v_fma_f32 v187, v187, s6, 0.5
	v_fma_f32 v188, v188, s6, 0.5
	v_fma_f32 v189, v189, s6, 0.5
	v_max_f32_e32 v186, 1.5, v186
	v_max_f32_e32 v187, 1.5, v187
	v_max_f32_e32 v188, 1.5, v188
	v_max_f32_e32 v189, 1.5, v189
	v_cvt_u32_f32_e32 v186, v186
	v_cvt_u32_f32_e32 v187, v187
	v_cvt_u32_f32_sdwa v188, v188 dst_sel:WORD_1 dst_unused:UNUSED_PAD src0_sel:DWORD
	v_cvt_u32_f32_sdwa v189, v189 dst_sel:BYTE_3 dst_unused:UNUSED_PAD src0_sel:DWORD
	v_lshl_or_b32 v186, v187, 8, v186
	s_nop 0
	v_or3_b32 v186, v186, v188, v189
	global_store_dword v1, v186, s[58:59] offset:2048
	v_fma_f32 v190, v2, s5, v185
	v_fma_f32 v191, v3, s5, v71
	v_fma_f32 v192, v4, s5, v73
	v_fma_f32 v193, v5, s5, v75
	v_exp_f32_e32 v190, v190
	v_exp_f32_e32 v191, v191
	v_exp_f32_e32 v192, v192
	v_exp_f32_e32 v193, v193
	v_add_f32_e32 v190, 1.0, v190
	v_add_f32_e32 v191, 1.0, v191
	v_add_f32_e32 v192, 1.0, v192
	v_add_f32_e32 v193, 1.0, v193
	v_rcp_f32_e32 v190, v190
	v_rcp_f32_e32 v191, v191
	v_rcp_f32_e32 v192, v192
	v_rcp_f32_e32 v193, v193
	v_fma_f32 v190, v190, s6, 0.5
	v_fma_f32 v191, v191, s6, 0.5
	v_fma_f32 v192, v192, s6, 0.5
	v_fma_f32 v193, v193, s6, 0.5
	v_max_f32_e32 v190, 1.5, v190
	v_max_f32_e32 v191, 1.5, v191
	v_max_f32_e32 v192, 1.5, v192
	v_max_f32_e32 v193, 1.5, v193
	v_cvt_u32_f32_e32 v190, v190
	v_cvt_u32_f32_e32 v191, v191
	v_cvt_u32_f32_sdwa v192, v192 dst_sel:WORD_1 dst_unused:UNUSED_PAD src0_sel:DWORD
	v_cvt_u32_f32_sdwa v193, v193 dst_sel:BYTE_3 dst_unused:UNUSED_PAD src0_sel:DWORD
	v_lshl_or_b32 v190, v191, 8, v190
	s_nop 0
	v_or3_b32 v190, v190, v192, v193
	global_store_dword v1, v190, s[58:59] offset:3072
	s_mov_b64 s[46:47], -1
	s_mov_b32 s56, s23
	s_and_b64 vcc, exec, s[42:43]
	s_cbranch_vccnz .Lgp_tile
